# P4->P5 grid barrier skips the L2 writeback/invalidate when every workgroup verified at start that it runs on XCD (blockIdx%8) (H row panels are then produced and consumed on the same XCD); flag in the
# speedup vs baseline: 1.0038x; 1.0038x over previous
; __device__ __forceinline__ XcdBarrier xcd_barrier_post(unsigned* bar, volatile LAS unsigned* st) {
; __global__ void __launch_bounds__(512, 2) mk_fwd(Args args) {
;     extern __shared__ __attribute__((aligned(16))) unsigned char lds_raw[];
;     LAS unsigned char* lds = (LAS unsigned char*)lds_raw;
;     const int tid = threadIdx.x, lane = tid & 63, wave = __builtin_amdgcn_readfirstlane(tid >> 6);
;     const int G = gridDim.x, bx = blockIdx.x;
;     unsigned char* ws = args.ws;
;     const float* x = args.in[0]; const float* norm1_g = args.in[1]; const float* w_in = args.in[2]; const float* q_norm_g = args.in[3]; const float* k_norm_g = args.in[4];
;     const float* ln_v_g = args.in[5]; const float* ln_v_b = args.in[6]; const float* w_sp = args.in[7]; const float* b_sp = args.in[8];
;     const float* attn_out_g = args.in[9]; const float* gmlp_out_g = args.in[10]; const float* w_out = args.in[11]; const float* norm2_g = args.in[12];
;     const float* w_ff1 = args.in[13]; const float* w_ff2 = args.in[14];
;     float* out = args.out;
;     bf16_t* Win_t = (bf16_t*)(ws + WS_WIN); bf16_t* Wout_t = (bf16_t*)(ws + WS_WOUT); bf16_t* W1_t = (bf16_t*)(ws + WS_W1); bf16_t* W2_t = (bf16_t*)(ws + WS_W2);
;     float* ssq = (float*)(ws + WS_SSQ); float* ssqA = (float*)(ws + WS_SSQA); bf16_t* Wsb = (bf16_t*)(ws + WS_WSB);
;     bf16_t* XB = (bf16_t*)(ws + WS_XB); bf16_t* Qb = (bf16_t*)(ws + WS_Q); bf16_t* Kb = (bf16_t*)(ws + WS_K); bf16_t* Vt = (bf16_t*)(ws + WS_V);
;     bf16_t* Ub = (bf16_t*)(ws + WS_U); bf16_t* Gb = (bf16_t*)(ws + WS_G); bf16_t* MIX = (bf16_t*)(ws + WS_MIX); bf16_t* Hb = (bf16_t*)(ws + WS_H);
;     volatile LAS unsigned* MISC = (volatile LAS unsigned*)(lds + LDS_MISC);
;     if (tid < 16) MISC[tid] = 0u;
;     __syncthreads();
;     const XcdBarrier bar = xcd_barrier_post((unsigned*)(ws + WS_CTL), MISC);
;     ...
;     {
;         LAS float* scr = (LAS float*)(lds + wave * 16384);
;         const int gw = bx * 8 + wave, NGW = G * 8;
;         constexpr int I_IN = (DM / 64) * (NIN / 32), I_OUT = (DM / 64) * (DM / 32), I_1 = (DM / 64) * (FF / 32), I_2 = (FF / 64) * (DM / 32);
;         constexpr int NITEMS = I_IN + I_OUT + I_1 + I_2;
;         for (int it = gw; it < NITEMS; it += NGW) {
;             int r = it;
;             if (r < I_IN) { p0_transpose_item(w_in, DM, NIN, Win_t, nullptr, 0, scr, r, lane); continue; } r -= I_IN;
_Z6mk_fwd4Args:
	s_mov_b32 s32, 1
	s_load_dwordx2 s[84:85], s[0:1], 0x80
	s_load_dword s3, s[0:1], 0x88
	s_add_u32 s4, s0, 0x88
	s_addc_u32 s5, s1, 0
	v_readfirstlane_b32 s66, v0
	v_writelane_b32 v243, s4, 0
	v_cmp_gt_u32_e32 vcc, 16, v0
	s_nop 0
	v_writelane_b32 v243, s5, 1
	s_and_saveexec_b64 s[4:5], vcc
	v_lshl_add_u32 v1, v0, 2, 0
	v_add_u32_e32 v1, 0x267c0, v1
	v_mov_b32_e32 v2, 0
	ds_write_b32 v1, v2
	s_or_b64 exec, exec, s[4:5]
	s_waitcnt lgkmcnt(0)
	s_barrier
	s_getreg_b32 s4, hwreg(HW_REG_XCC_ID, 0, 4)
	s_and_b32 s67, s4, 15
	v_cmp_ne_u32_e64 s[86:87], 0, v0
	v_cmp_eq_u32_e64 s[6:7], 0, v0
	s_mov_b64 s[4:5], exec
	s_nop 0
	v_writelane_b32 v243, s6, 2
	s_nop 1
	v_writelane_b32 v243, s7, 3
	s_and_b64 s[6:7], s[4:5], s[6:7]
	s_mov_b64 exec, s[6:7]
	s_cbranch_execz .LBB0_5
	s_mov_b64 s[6:7], exec
	v_mbcnt_lo_u32_b32 v1, s6, 0
	v_mbcnt_hi_u32_b32 v1, s7, v1
	v_cmp_eq_u32_e32 vcc, 0, v1
	s_and_b64 s[8:9], exec, vcc
	s_mov_b64 exec, s[8:9]
	s_cbranch_execz .LBB0_5
	s_lshl_b32 s8, s67, 8
	s_bcnt1_i32_b64 s6, s[6:7]
	v_mov_b32_e32 v1, s8
	v_mov_b32_e32 v2, s6
	global_atomic_add v1, v2, s[84:85] offset:1024
	s_and_b32 s9, s2, 7
	s_cmp_lg_u32 s9, s67
	s_cselect_b32 s9, 1, 0
	s_cmp_lg_u32 s3, 0x100
	s_cselect_b32 s8, 1, 0
	s_or_b32 s9, s9, s8
	s_cmp_eq_u32 s9, 0
	s_cbranch_scc1 .Lxcd_map_ok
	v_mov_b32_e32 v3, 0x3800
	v_mov_b32_e32 v4, 1
	global_store_dword v3, v4, s[84:85] sc0 sc1
.Lxcd_map_ok:
.LBB0_5:
	s_or_b64 exec, exec, s[4:5]
	s_load_dwordx16 s[4:19], s[0:1], 0x0
	s_lshr_b32 s92, s66, 6
	s_load_dwordx16 s[40:55], s[0:1], 0x40
	v_and_b32_e32 v201, 63, v0
	v_and_b32_e32 v1, 31, v0
	s_waitcnt lgkmcnt(0)
	v_writelane_b32 v243, s4, 4
	s_nop 1
	v_writelane_b32 v243, s5, 5
	v_writelane_b32 v243, s6, 6
	v_writelane_b32 v243, s7, 7
	v_writelane_b32 v243, s8, 8
	v_writelane_b32 v243, s9, 9
	v_writelane_b32 v243, s10, 10
	v_writelane_b32 v243, s11, 11
	v_writelane_b32 v243, s12, 12
	v_writelane_b32 v243, s13, 13
	v_writelane_b32 v243, s14, 14
	v_writelane_b32 v243, s15, 15
	v_writelane_b32 v243, s16, 16
	v_writelane_b32 v243, s17, 17
	v_writelane_b32 v243, s18, 18
	v_writelane_b32 v243, s19, 19
	s_add_u32 s6, s84, 0x100000
	s_addc_u32 s7, s85, 0
	s_add_u32 s94, s84, 0x600000
	s_addc_u32 s95, s85, 0
	s_add_u32 s88, s84, 0x800000
	s_addc_u32 s89, s85, 0
	s_add_u32 s90, s84, 0x1000000
	s_addc_u32 s91, s85, 0
	s_lshl_b32 s0, s2, 3
	s_add_i32 s8, s92, s0
	s_lshl_b32 s10, s3, 3
	s_cmpk_gt_i32 s8, 0x16ff
	s_cbranch_scc1 .LBB0_25
	s_lshl_b32 s0, s92, 14
	s_add_i32 s0, s0, 0
	v_lshrrev_b32_e32 v32, 5, v201
	v_and_b32_e32 v4, 7, v0
	v_lshrrev_b32_e32 v34, 3, v201
	s_cmp_lg_u64 s[48:49], 0
	v_lshlrev_b32_e32 v10, 2, v1
	v_mov_b32_e32 v11, 0
	v_mul_u32_u24_e32 v2, 0x84, v32
	v_mul_u32_u24_e32 v5, 0x420, v4
	v_lshlrev_b32_e32 v6, 2, v34
	s_cselect_b64 s[4:5], -1, 0
	s_cmp_lg_u64 s[42:43], 0
	v_readlane_b32 s16, v243, 4
	v_add3_u32 v33, s0, v10, v2
	v_lshlrev_b32_e32 v2, 4, v4
	v_mov_b32_e32 v3, v11
	v_add3_u32 v35, s0, v5, v6
	v_lshlrev_b32_e32 v4, 5, v4
	v_mov_b32_e32 v5, v11
	s_cselect_b64 s[12:13], -1, 0
	v_readlane_b32 s18, v243, 6
	v_readlane_b32 s19, v243, 7
	v_readlane_b32 s20, v243, 8
	v_readlane_b32 s21, v243, 9
	s_lshl_b32 s0, s8, 1
	s_mov_b32 s1, 0
	v_lshl_add_u64 v[12:13], s[52:53], 0, v[10:11]
	v_lshl_add_u64 v[14:15], s[90:91], 0, v[2:3]
	v_or_b32_e32 v36, 8, v34
	v_or_b32_e32 v37, 16, v34
	v_or_b32_e32 v38, 24, v34
	v_lshl_add_u64 v[16:17], s[50:51], 0, v[10:11]
	v_lshl_add_u64 v[18:19], s[48:49], 0, v[4:5]
	v_lshl_add_u64 v[20:21], s[46:47], 0, v[10:11]
	v_lshl_add_u64 v[22:23], s[42:43], 0, v[4:5]
	v_lshl_add_u64 v[24:25], s[20:21], 0, v[10:11]
	v_lshl_add_u64 v[26:27], s[6:7], 0, v[2:3]
	v_lshl_add_u64 v[28:29], s[88:89], 0, v[2:3]
	v_lshl_add_u64 v[30:31], s[94:95], 0, v[2:3]
	s_lshl_b32 s9, s8, 5
	s_lshl_b32 s11, s10, 5
	s_add_i32 s18, s0, 0x1e200
	s_lshl_b32 s19, s10, 1
	s_xor_b64 s[12:13], s[12:13], -1
	s_movk_i32 s20, 0x2800
	v_add_u32_e32 v39, 0x400, v33
	v_add_u32_e32 v40, 0x800, v33
	v_add_u32_e32 v41, 0xc00, v33
	v_add_u32_e32 v42, 0x1000, v33
	v_add_u32_e32 v43, 0x1400, v33
	v_add_u32_e32 v44, 0x1800, v33
	v_add_u32_e32 v45, 0x1c00, v33
	s_mov_b32 s21, s8
	v_readlane_b32 s17, v243, 5
	v_readlane_b32 s22, v243, 10
	v_readlane_b32 s23, v243, 11
	v_readlane_b32 s24, v243, 12
	v_readlane_b32 s25, v243, 13
	v_readlane_b32 s26, v243, 14
	v_readlane_b32 s27, v243, 15
	v_readlane_b32 s28, v243, 16
	v_readlane_b32 s29, v243, 17
	v_readlane_b32 s30, v243, 18
	v_readlane_b32 s31, v243, 19
	s_branch .LBB0_8

; #define PG8_WAIT_V(n) asm volatile("s_waitcnt vmcnt(" #n ")" ::: "memory")
; #define PG8_BAR __builtin_amdgcn_s_barrier()
; template <class Epi, class Sched>
; __device__ __forceinline__ void gemm_phase(LAS unsigned char* lds, const Gemm g, const Sched& S, const Epi& E) {
;     int tid_ = threadIdx.x; asm volatile("" : "+v"(tid_));
;     const int tid = tid_, wid = __builtin_amdgcn_readfirstlane(tid >> 6), lane = tid & 63, wr = wid >> 2, wc = wid & 3, fr = lane & 15, fq = lane >> 4;
;     const int K = g.K, nt = K / BK;
;     unsigned voffA[2], voffB[2];
; #pragma unroll
;     for (int i = 0; i < 2; ++i) { int R, C; stage_rc(tid * 16 + i * 8192, R, C);
;         const int Ra = 128 * (R >> 6) + (R & 63);
;         const int Rb = Epi::HEADPERM ? (64 * (R >> 5) + perm32(R & 31)) : ((R & ~31) + perm32(R & 31));
;         voffA[i] = (unsigned)(Ra * g.lda + C) * 2u; voffB[i] = (unsigned)(Rb * K + C) * 2u; }
;     ...
;     const char* cA = (const char*)g.A + (size_t)cur.pm * tstep; const char* cB = (const char*)g.Bt + (size_t)cur.pn * tstep;
;     PG8_STAGE(PG8_SB(0, 0), cB, voffB); PG8_STAGE(PG8_SB(0, 1), cB + hstepB, voffB); PG8_STAGE(PG8_SA(0, 0), cA, voffA); PG8_STAGE(PG8_SA(0, 1), cA + hstepA, voffA);
;     if (wr == 1) PG8_BAR;
;     PG8_WAIT_V(2); PG8_BAR;
;     PG8_STAGE(PG8_SB(1, 0), cB + kstep, voffB); PG8_STAGE(PG8_SA(1, 0), cA + kstepA, voffA); PG8_STAGE(PG8_SB(1, 1), cB + hstepB + kstep, voffB);
.LBB0_699:
	v_readlane_b32 s0, v243, 4
	v_mov_b32_e32 v2, v0
	v_readlane_b32 s1, v243, 5
	s_andn2_b64 vcc, exec, s[0:1]
	v_readfirstlane_b32 s1, v2
	s_cbranch_vccnz .LBB0_719
	v_mov_b32_e32 v240, 0x3800
	global_load_dword v241, v240, s[84:85] sc1
	s_waitcnt vmcnt(0)
	v_readfirstlane_b32 s32, v241
	s_mov_b32 s100, -1
	v_bfe_i32 v5, v2, 27, 1
	v_lshlrev_b32_e32 v3, 4, v2
	v_lshrrev_b32_e32 v5, 22, v5
	v_add_u32_e32 v5, v3, v5
	v_and_b32_e32 v5, 0xfffffc00, v5
	v_sub_u32_e32 v5, v3, v5
	v_ashrrev_i32_e32 v4, 31, v2
	v_lshrrev_b32_e32 v6, 4, v5
	v_lshrrev_b32_e32 v4, 26, v4
	v_bitop3_b32 v5, v6, v5, 32 bitop3:0x6c
	v_add_u32_e32 v4, v2, v4
	v_ashrrev_i32_e32 v7, 31, v5
	v_ashrrev_i32_e32 v4, 6, v4
	v_lshrrev_b32_e32 v7, 26, v7
	v_lshlrev_b32_e32 v6, 3, v4
	v_add_u32_e32 v7, v5, v7
	v_and_b32_e32 v6, -16, v6
	v_ashrrev_i32_e32 v8, 6, v7
	v_and_b32_e32 v7, 0xc0, v7
	v_add_u32_e32 v6, v8, v6
	v_sub_u32_e32 v5, v5, v7
	v_lshlrev_b32_e32 v4, 5, v4
	v_ashrrev_i16_sdwa v5, v164, sext(v5) dst_sel:DWORD dst_unused:UNUSED_PAD src0_sel:DWORD src1_sel:BYTE_0
	v_lshlrev_b32_e32 v7, 1, v6
	v_and_b32_e32 v9, 63, v6
	s_mov_b32 s4, 0x1fff80
	v_lshrrev_b32_e32 v10, 2, v6
	v_and_b32_e32 v8, 3, v8
	s_mov_b32 s5, 0x1fffe0
	v_and_b32_e32 v4, 32, v4
	v_bfe_i32 v5, v5, 0, 16
	v_and_or_b32 v9, v7, s4, v9
	v_and_b32_e32 v7, 24, v7
	v_and_b32_e32 v10, 4, v10
	v_and_or_b32 v6, v6, s5, v8
	v_or3_b32 v6, v6, v10, v7
	v_add_lshl_u32 v4, v4, v5, 1
	v_add_u32_e32 v3, 0x2000, v3
	v_lshl_add_u32 v165, v9, 11, v4
	v_lshl_add_u32 v166, v6, 11, v4
	v_ashrrev_i32_e32 v4, 31, v3
	v_lshrrev_b32_e32 v4, 22, v4
	v_add_u32_e32 v4, v3, v4
	v_ashrrev_i32_e32 v4, 10, v4
	v_mul_i32_i24_e32 v5, 0x400, v4
	v_sub_u32_e32 v3, v3, v5
	v_lshrrev_b32_e32 v5, 4, v3
	v_bitop3_b32 v3, v5, v3, 32 bitop3:0x6c
	v_ashrrev_i32_e32 v6, 31, v3
	v_lshrrev_b32_e32 v6, 26, v6
	v_lshlrev_b32_e32 v5, 3, v4
	v_add_u32_e32 v6, v3, v6
	v_and_b32_e32 v5, -16, v5
	v_ashrrev_i32_e32 v7, 6, v6
	v_and_b32_e32 v6, 0xc0, v6
	s_ashr_i32 s0, s1, 6
	v_add_u32_e32 v5, v7, v5
	v_sub_u32_e32 v3, v3, v6
	v_and_b32_e32 v7, 3, v7
	v_lshlrev_b32_e32 v4, 5, v4
	v_ashrrev_i16_sdwa v3, v164, sext(v3) dst_sel:DWORD dst_unused:UNUSED_PAD src0_sel:DWORD src1_sel:BYTE_0
	v_lshlrev_b32_e32 v6, 1, v5
	v_and_b32_e32 v8, 63, v5
	v_lshrrev_b32_e32 v9, 2, v5
	v_and_or_b32 v5, v5, s5, v7
	s_lshl_b32 s5, s0, 10
	v_and_b32_e32 v4, 32, v4
	v_bfe_i32 v3, v3, 0, 16
	v_and_or_b32 v8, v6, s4, v8
	v_and_b32_e32 v6, 24, v6
	v_and_b32_e32 v9, 4, v9
	v_readlane_b32 s6, v243, 28
	s_add_i32 s35, s5, 0
	v_or3_b32 v5, v5, v9, v6
	v_add_lshl_u32 v3, v4, v3, 1
	s_add_i32 s10, s34, s6
	s_add_i32 s64, s35, 0x10000
	s_mov_b32 m0, s64
	s_nop 0
	global_load_lds_dwordx4 v166, s[70:71]
	v_lshl_add_u32 v168, v5, 11, v3
	s_ashr_i32 s11, s10, 31
	s_add_i32 s65, s35, 0x12000
	s_mov_b32 m0, s65
	s_nop 0
	global_load_lds_dwordx4 v168, s[70:71]
	v_readlane_b32 s8, v243, 24
	s_ashr_i32 s4, s1, 8
	s_lshl_b64 s[6:7], s[10:11], 19
	s_add_i32 s38, s35, 0x14000
	v_readlane_b32 s9, v243, 25
	s_mov_b32 m0, s38
	s_nop 0
	global_load_lds_dwordx4 v166, s[8:9]
	s_add_i32 s39, s35, 0x16000
	s_mov_b32 m0, s39
	s_nop 0
	global_load_lds_dwordx4 v168, s[8:9]
	s_add_u32 s6, s42, s6
	s_addc_u32 s7, s43, s7
	s_mov_b32 m0, s35
	s_nop 0
	global_load_lds_dwordx4 v165, s[6:7]
	s_add_i32 s48, s35, 0x2000
	s_add_i32 s49, s35, 0x4000
	v_lshl_add_u32 v167, v8, 11, v3
	s_mov_b32 m0, s48
	s_nop 0
	global_load_lds_dwordx4 v167, s[6:7]
	s_add_u32 s8, s6, 0x20000
	s_addc_u32 s9, s7, 0
	s_mov_b32 m0, s49
	s_nop 0
	global_load_lds_dwordx4 v165, s[8:9]
	s_add_i32 s25, s35, 0x6000
	s_mov_b32 m0, s25
	s_nop 0
	global_load_lds_dwordx4 v167, s[8:9]
	s_cmp_eq_u32 s4, 1
	s_cselect_b64 s[96:97], -1, 0
	s_cmp_lg_u32 s4, 1
	s_cbranch_scc1 .LBB0_702
	s_barrier

; __device__ __forceinline__ unsigned xb_ld(unsigned* p)              { return __hip_atomic_load(p, __ATOMIC_RELAXED, __HIP_MEMORY_SCOPE_AGENT); }
; #define XB_SPIN(cond, bar) do { unsigned _sp = 0; while (cond) { __builtin_amdgcn_s_sleep(1); \
;     if ((++_sp & 255u) == 0u) { if (xb_ld(&(bar)[XB_TMO])) break; if (_sp > XB_SPIN_CAP) { atomicAdd(&(bar)[XB_TMO], 1u); break; } } } } while (0)
; __device__ __forceinline__ void xcd_barrier(const XcdBarrier& b) {
;     ...
;             XB_SPIN(xb_ld(&bar[XB_XGEN(b.x)]) == gen, bar);
;             __builtin_amdgcn_fence(__ATOMIC_ACQUIRE, "agent");
;             asm volatile("s_waitcnt vmcnt(0)" ::: "memory");
.LBB0_748:
	s_or_b64 exec, exec, s[6:7]
	s_waitcnt vmcnt(0)
	s_cmp_eq_u32 s32, 0
	s_cbranch_scc1 .Lh_local_2
	buffer_inv sc1

; __device__ __forceinline__ unsigned xb_add(unsigned* p, unsigned v) { return __hip_atomic_fetch_add(p, v, __ATOMIC_RELAXED, __HIP_MEMORY_SCOPE_AGENT); }
; __device__ __forceinline__ void xcd_barrier(const XcdBarrier& b) {
;     ...
;         if (old + 1u == (gen + 1u) * nloc) {
;             __builtin_amdgcn_fence(__ATOMIC_RELEASE, "agent");
;             asm volatile("s_waitcnt vmcnt(0)" ::: "memory");
;             const unsigned og = xb_add(&bar[XB_TOP], 1u);
;             const unsigned tg = og / nx;
.LBB0_749:
	s_andn2_saveexec_b64 s[4:5], s[4:5]
	s_cbranch_execz .LBB0_767
	s_mov_b64 s[4:5], exec
	s_cmp_eq_u32 s32, 0
	s_cbranch_scc1 .Lh_local_1
	buffer_wbl2 sc1
.Lh_local_1:
	s_waitcnt lgkmcnt(0)
	s_waitcnt vmcnt(0)
	v_mbcnt_lo_u32_b32 v3, s4, 0
	v_mbcnt_hi_u32_b32 v3, s5, v3
	v_cmp_eq_u32_e32 vcc, 0, v3
	s_and_saveexec_b64 s[6:7], vcc
	s_cbranch_execz .LBB0_752
	s_bcnt1_i32_b64 s4, s[4:5]
	v_mov_b32_e32 v4, s4
	v_readlane_b32 s4, v243, 63
	v_readlane_b32 s5, v242, 0
	s_nop 4
	global_atomic_add v4, v135, v4, s[4:5] sc0

; __device__ __forceinline__ unsigned xb_ld(unsigned* p)              { return __hip_atomic_load(p, __ATOMIC_RELAXED, __HIP_MEMORY_SCOPE_AGENT); }
; __device__ __forceinline__ unsigned xb_add(unsigned* p, unsigned v) { return __hip_atomic_fetch_add(p, v, __ATOMIC_RELAXED, __HIP_MEMORY_SCOPE_AGENT); }
; #define XB_SPIN(cond, bar) do { unsigned _sp = 0; while (cond) { __builtin_amdgcn_s_sleep(1); \
;     if ((++_sp & 255u) == 0u) { if (xb_ld(&(bar)[XB_TMO])) break; if (_sp > XB_SPIN_CAP) { atomicAdd(&(bar)[XB_TMO], 1u); break; } } } } while (0)
; __device__ __forceinline__ void xcd_barrier(const XcdBarrier& b) {
;     ...
;             else XB_SPIN(xb_ld(&bar[XB_TOPGEN]) == tg, bar);
;             __builtin_amdgcn_fence(__ATOMIC_ACQUIRE, "agent");
;             xb_add(&bar[XB_XGEN(b.x)], 1u);
;             asm volatile("s_waitcnt vmcnt(0)" ::: "memory");
.LBB0_766:
	s_or_b64 exec, exec, s[4:5]
	s_waitcnt vmcnt(0)
	s_cmp_eq_u32 s32, 0
	s_cbranch_scc1 .Lh_local_0
	buffer_inv sc1
.Lh_local_0:
	global_atomic_add v[132:133], v164, off
	s_waitcnt vmcnt(0)
